# v63 + RWKV waves 4-7 at priority 2 while computing addresses/issuing the XF operand reads right after the chunk barrier
# speedup vs baseline: 1.0033x; 1.0033x over previous
; #define LAS __attribute__((address_space(3)))
; __device__ __forceinline__ f32x4 mfma16(bf16x8 a, bf16x8 b, f32x4 c) { return __builtin_amdgcn_mfma_f32_16x16x32_bf16(a, b, c, 0, 0, 0); }
; __device__ __forceinline__ void rwkv_chunk_item(const P& p, const Ctx& c, int seg, int w, bool save) {
;     ...
;         if (c.wv >= 4) {
;             f32x4 Xt = (f32x4){0.f, 0.f, 0.f, 0.f};
; #pragma unroll
;             for (int kk = 0; kk < 2; ++kk) { const bf16x8 a = *(const LAS bf16x8*)(S0I + (mtq * 16 + l15) * 72 + kk * 32 + quad * 8);
;                 Xt = mfma16(a, *(const LAS bf16x8*)(EA + l15 * 72 + kk * 32 + quad * 8), Xt); Zt = mfma16(a, *(const LAS bf16x8*)(EA + (16 + l15) * 72 + kk * 32 + quad * 8), Zt); }
;             Xt = mfma16(*(const LAS bf16x8*)(UV + (mtq * 16 + l15) * 40 + quad * 8), *(const LAS bf16x8*)(MT1 + l15 * 40 + quad * 8), Xt);
; #pragma unroll
;             for (int jj = 0; jj < 4; ++jj) XF[(mtq * 16 + quad * 4 + jj) * 17 + l15] = Xt[jj];
;         }
.LBB0_888:
	s_and_b32 s87, s86, 1
	s_mul_i32 s2, s87, 0x5c00
	s_add_i32 s88, s2, 0
	v_add_u32_e32 v45, s35, v82
	v_lshlrev_b32_e32 v85, 4, v83
	v_mul_lo_u32 v84, v82, s64
	v_mov_b32_e32 v22, 0
	s_andn2_b64 vcc, exec, s[56:57]
	v_mul_lo_u32 v87, v45, s64
	v_add3_u32 v86, s88, v84, v85
	v_mov_b32_e32 v23, 0
	v_mov_b32_e32 v24, 0
	v_mov_b32_e32 v25, 0
	s_cbranch_vccnz .LBB0_890
	s_setprio 2
	v_mul_lo_u32 v22, v45, s63
	v_add3_u32 v45, 0, v22, v85
	v_mul_lo_u32 v22, v82, s63
	v_add3_u32 v54, s88, v22, v85
	v_add3_u32 v129, s88, v87, v85
	ds_read_b128 v[22:25], v45 offset:47104
	ds_read_b128 v[46:49], v54
	ds_read_b128 v[88:91], v45 offset:47168
	ds_read_b128 v[92:95], v54 offset:64
	ds_read_b128 v[96:99], v129 offset:14336
	ds_read_b128 v[100:103], v86 offset:19456
	ds_read_b128 v[50:53], v54 offset:2304
	ds_read_b128 v[124:127], v54 offset:2368
	s_setprio 0
	s_movk_i32 s2, 0x44
	v_lshl_add_u32 v45, v83, 2, s35
	v_lshlrev_b32_e32 v54, 2, v82
	v_mul_lo_u32 v45, v45, s2
	v_add3_u32 v45, 0, v54, v45
	v_add_u32_e32 v45, 0xdc00, v45
	s_waitcnt lgkmcnt(6)
	v_mfma_f32_16x16x32_bf16 v[46:49], v[22:25], v[46:49], 0
	s_waitcnt lgkmcnt(4)
	v_mfma_f32_16x16x32_bf16 v[46:49], v[88:91], v[92:95], v[46:49]
	s_waitcnt lgkmcnt(2)
	v_mfma_f32_16x16x32_bf16 v[46:49], v[96:99], v[100:103], v[46:49]
	s_nop 7
	s_nop 1
	ds_write2_b32 v45, v46, v47 offset1:17
	ds_write2_b32 v45, v48, v49 offset0:34 offset1:51
	s_waitcnt lgkmcnt(2)
	v_mfma_f32_16x16x32_bf16 v[22:25], v[22:25], v[50:53], 0
	v_mfma_f32_16x16x32_bf16 v[22:25], v[88:91], v[124:127], v[22:25]
